# gdn_prep forward substitution on the f32 matrix cores (v_mfma_f32_16x16x4_f32): blocked 16x16, explicit diagonal-block inverses, operands kept in the MFMA result layout; f32 operands and accumulation
# speedup vs baseline: 1.0152x; 1.0152x over previous
.LBB0_309:
	s_or_b64 exec, exec, s[0:1]
	ds_write_b32 v167, v0 offset:16576
	v_mul_f32_e32 v0, v15, v2
	v_cvt_pk_bf16_f32 v0, v0, s0
	v_readlane_b32 s0, v250, 44
	v_readlane_b32 s1, v250, 45
	v_add_co_u32_e32 v2, vcc, 0x10000, v24
	s_nop 0
	v_cndmask_b32_e64 v0, v0, 0, s[0:1]
	v_addc_co_u32_e32 v3, vcc, 0, v25, vcc
	global_store_short v[2:3], v0, off offset:96
	s_waitcnt lgkmcnt(0)
	s_barrier
	v_and_b32_e32 v3, 63, v162
	v_lshrrev_b32_e32 v2, 6, v162
	v_and_b32_e32 v0, 15, v3
	v_readfirstlane_b32 s14, v2
	v_lshrrev_b32_e32 v2, 4, v3
	s_mov_b64 s[68:69], exec
	s_mov_b64 exec, 0xffff
	s_mul_i32 s15, s14, 0x1040
	s_add_u32 s15, s15, 0x4000
	v_mov_b32_e32 v3, s15
	ds_read_b128 v[40:43], v3 offset:256
	v_cmp_eq_u32_e32 vcc, 0, v0
	s_nop 1
	v_cndmask_b32_e64 v8, 0, 1.0, vcc
	v_cmp_eq_u32_e32 vcc, 1, v0
	s_nop 1
	v_cndmask_b32_e64 v9, 0, 1.0, vcc
	v_cmp_eq_u32_e32 vcc, 2, v0
	s_nop 1
	v_cndmask_b32_e64 v10, 0, 1.0, vcc
	v_cmp_eq_u32_e32 vcc, 3, v0
	s_nop 1
	v_cndmask_b32_e64 v11, 0, 1.0, vcc
	v_cmp_eq_u32_e32 vcc, 4, v0
	s_nop 1
	v_cndmask_b32_e64 v12, 0, 1.0, vcc
	v_cmp_eq_u32_e32 vcc, 5, v0
	s_nop 1
	v_cndmask_b32_e64 v13, 0, 1.0, vcc
	v_cmp_eq_u32_e32 vcc, 6, v0
	s_nop 1
	v_cndmask_b32_e64 v14, 0, 1.0, vcc
	v_cmp_eq_u32_e32 vcc, 7, v0
	s_nop 1
	v_cndmask_b32_e64 v15, 0, 1.0, vcc
	v_cmp_eq_u32_e32 vcc, 8, v0
	s_nop 1
	v_cndmask_b32_e64 v16, 0, 1.0, vcc
	v_cmp_eq_u32_e32 vcc, 9, v0
	s_nop 1
	v_cndmask_b32_e64 v17, 0, 1.0, vcc
	v_cmp_eq_u32_e32 vcc, 10, v0
	s_nop 1
	v_cndmask_b32_e64 v18, 0, 1.0, vcc
	v_cmp_eq_u32_e32 vcc, 11, v0
	s_nop 1
	v_cndmask_b32_e64 v19, 0, 1.0, vcc
	v_cmp_eq_u32_e32 vcc, 12, v0
	s_nop 1
	v_cndmask_b32_e64 v20, 0, 1.0, vcc
	v_cmp_eq_u32_e32 vcc, 13, v0
	s_nop 1
	v_cndmask_b32_e64 v21, 0, 1.0, vcc
	v_cmp_eq_u32_e32 vcc, 14, v0
	s_nop 1
	v_cndmask_b32_e64 v22, 0, 1.0, vcc
	v_cmp_eq_u32_e32 vcc, 15, v0
	s_nop 1
	v_cndmask_b32_e64 v23, 0, 1.0, vcc
	ds_read_b128 v[24:27], v3 offset:512
	s_waitcnt lgkmcnt(1)
	v_fma_f32 v9, -v40, v8, v9
	ds_read_b128 v[40:43], v3 offset:768
	s_waitcnt lgkmcnt(1)
	v_fma_f32 v10, -v24, v8, v10
	v_fma_f32 v10, -v25, v9, v10
	ds_read_b128 v[24:27], v3 offset:1024
	s_waitcnt lgkmcnt(1)
	v_fma_f32 v11, -v40, v8, v11
	v_fma_f32 v11, -v41, v9, v11
	v_fma_f32 v11, -v42, v10, v11
	ds_read_b128 v[40:43], v3 offset:1280
	ds_read_b128 v[44:47], v3 offset:1296
	s_waitcnt lgkmcnt(2)
	v_fma_f32 v12, -v24, v8, v12
	v_fma_f32 v12, -v25, v9, v12
	v_fma_f32 v12, -v26, v10, v12
	v_fma_f32 v12, -v27, v11, v12
	ds_read_b128 v[24:27], v3 offset:1536
	ds_read_b128 v[28:31], v3 offset:1552
	s_waitcnt lgkmcnt(3)
	v_fma_f32 v13, -v40, v8, v13
	v_fma_f32 v13, -v41, v9, v13
	v_fma_f32 v13, -v42, v10, v13
	v_fma_f32 v13, -v43, v11, v13
	s_waitcnt lgkmcnt(2)
	v_fma_f32 v13, -v44, v12, v13
	ds_read_b128 v[40:43], v3 offset:1792
	ds_read_b128 v[44:47], v3 offset:1808
	s_waitcnt lgkmcnt(3)
	v_fma_f32 v14, -v24, v8, v14
	v_fma_f32 v14, -v25, v9, v14
	v_fma_f32 v14, -v26, v10, v14
	v_fma_f32 v14, -v27, v11, v14
	s_waitcnt lgkmcnt(2)
	v_fma_f32 v14, -v28, v12, v14
	v_fma_f32 v14, -v29, v13, v14
	ds_read_b128 v[24:27], v3 offset:2048
	ds_read_b128 v[28:31], v3 offset:2064
	s_waitcnt lgkmcnt(3)
	v_fma_f32 v15, -v40, v8, v15
	v_fma_f32 v15, -v41, v9, v15
	v_fma_f32 v15, -v42, v10, v15
	v_fma_f32 v15, -v43, v11, v15
	s_waitcnt lgkmcnt(2)
	v_fma_f32 v15, -v44, v12, v15
	v_fma_f32 v15, -v45, v13, v15
	v_fma_f32 v15, -v46, v14, v15
	ds_read_b128 v[40:43], v3 offset:2304
	ds_read_b128 v[44:47], v3 offset:2320
	ds_read_b128 v[48:51], v3 offset:2336
	s_waitcnt lgkmcnt(4)
	v_fma_f32 v16, -v24, v8, v16
	v_fma_f32 v16, -v25, v9, v16
	v_fma_f32 v16, -v26, v10, v16
	v_fma_f32 v16, -v27, v11, v16
	s_waitcnt lgkmcnt(3)
	v_fma_f32 v16, -v28, v12, v16
	v_fma_f32 v16, -v29, v13, v16
	v_fma_f32 v16, -v30, v14, v16
	v_fma_f32 v16, -v31, v15, v16
	ds_read_b128 v[24:27], v3 offset:2560
	ds_read_b128 v[28:31], v3 offset:2576
	ds_read_b128 v[32:35], v3 offset:2592
	s_waitcnt lgkmcnt(5)
	v_fma_f32 v17, -v40, v8, v17
	v_fma_f32 v17, -v41, v9, v17
	v_fma_f32 v17, -v42, v10, v17
	v_fma_f32 v17, -v43, v11, v17
	s_waitcnt lgkmcnt(4)
	v_fma_f32 v17, -v44, v12, v17
	v_fma_f32 v17, -v45, v13, v17
	v_fma_f32 v17, -v46, v14, v17
	v_fma_f32 v17, -v47, v15, v17
	s_waitcnt lgkmcnt(3)
	v_fma_f32 v17, -v48, v16, v17
	ds_read_b128 v[40:43], v3 offset:2816
	ds_read_b128 v[44:47], v3 offset:2832
	ds_read_b128 v[48:51], v3 offset:2848
	s_waitcnt lgkmcnt(5)
	v_fma_f32 v18, -v24, v8, v18
	v_fma_f32 v18, -v25, v9, v18
	v_fma_f32 v18, -v26, v10, v18
	v_fma_f32 v18, -v27, v11, v18
	s_waitcnt lgkmcnt(4)
	v_fma_f32 v18, -v28, v12, v18
	v_fma_f32 v18, -v29, v13, v18
	v_fma_f32 v18, -v30, v14, v18
	v_fma_f32 v18, -v31, v15, v18
	s_waitcnt lgkmcnt(3)
	v_fma_f32 v18, -v32, v16, v18
	v_fma_f32 v18, -v33, v17, v18
	ds_read_b128 v[24:27], v3 offset:3072
	ds_read_b128 v[28:31], v3 offset:3088
	ds_read_b128 v[32:35], v3 offset:3104
	s_waitcnt lgkmcnt(5)
	v_fma_f32 v19, -v40, v8, v19
	v_fma_f32 v19, -v41, v9, v19
	v_fma_f32 v19, -v42, v10, v19
	v_fma_f32 v19, -v43, v11, v19
	s_waitcnt lgkmcnt(4)
	v_fma_f32 v19, -v44, v12, v19
	v_fma_f32 v19, -v45, v13, v19
	v_fma_f32 v19, -v46, v14, v19
	v_fma_f32 v19, -v47, v15, v19
	s_waitcnt lgkmcnt(3)
	v_fma_f32 v19, -v48, v16, v19
	v_fma_f32 v19, -v49, v17, v19
	v_fma_f32 v19, -v50, v18, v19
	ds_read_b128 v[40:43], v3 offset:3328
	ds_read_b128 v[44:47], v3 offset:3344
	ds_read_b128 v[48:51], v3 offset:3360
	ds_read_b128 v[52:55], v3 offset:3376
	s_waitcnt lgkmcnt(6)
	v_fma_f32 v20, -v24, v8, v20
	v_fma_f32 v20, -v25, v9, v20
	v_fma_f32 v20, -v26, v10, v20
	v_fma_f32 v20, -v27, v11, v20
	s_waitcnt lgkmcnt(5)
	v_fma_f32 v20, -v28, v12, v20
	v_fma_f32 v20, -v29, v13, v20
	v_fma_f32 v20, -v30, v14, v20
	v_fma_f32 v20, -v31, v15, v20
	s_waitcnt lgkmcnt(4)
	v_fma_f32 v20, -v32, v16, v20
	v_fma_f32 v20, -v33, v17, v20
	v_fma_f32 v20, -v34, v18, v20
	v_fma_f32 v20, -v35, v19, v20
	ds_read_b128 v[24:27], v3 offset:3584
	ds_read_b128 v[28:31], v3 offset:3600
	ds_read_b128 v[32:35], v3 offset:3616
	ds_read_b128 v[36:39], v3 offset:3632
	s_waitcnt lgkmcnt(7)
	v_fma_f32 v21, -v40, v8, v21
	v_fma_f32 v21, -v41, v9, v21
	v_fma_f32 v21, -v42, v10, v21
	v_fma_f32 v21, -v43, v11, v21
	s_waitcnt lgkmcnt(6)
	v_fma_f32 v21, -v44, v12, v21
	v_fma_f32 v21, -v45, v13, v21
	v_fma_f32 v21, -v46, v14, v21
	v_fma_f32 v21, -v47, v15, v21
	s_waitcnt lgkmcnt(5)
	v_fma_f32 v21, -v48, v16, v21
	v_fma_f32 v21, -v49, v17, v21
	v_fma_f32 v21, -v50, v18, v21
	v_fma_f32 v21, -v51, v19, v21
	s_waitcnt lgkmcnt(4)
	v_fma_f32 v21, -v52, v20, v21
	ds_read_b128 v[40:43], v3 offset:3840
	ds_read_b128 v[44:47], v3 offset:3856
	ds_read_b128 v[48:51], v3 offset:3872
	ds_read_b128 v[52:55], v3 offset:3888
	s_waitcnt lgkmcnt(7)
	v_fma_f32 v22, -v24, v8, v22
	v_fma_f32 v22, -v25, v9, v22
	v_fma_f32 v22, -v26, v10, v22
	v_fma_f32 v22, -v27, v11, v22
	s_waitcnt lgkmcnt(6)
	v_fma_f32 v22, -v28, v12, v22
	v_fma_f32 v22, -v29, v13, v22
	v_fma_f32 v22, -v30, v14, v22
	v_fma_f32 v22, -v31, v15, v22
	s_waitcnt lgkmcnt(5)
	v_fma_f32 v22, -v32, v16, v22
	v_fma_f32 v22, -v33, v17, v22
	v_fma_f32 v22, -v34, v18, v22
	v_fma_f32 v22, -v35, v19, v22
	s_waitcnt lgkmcnt(4)
	v_fma_f32 v22, -v36, v20, v22
	v_fma_f32 v22, -v37, v21, v22
	s_waitcnt lgkmcnt(3)
	v_fma_f32 v23, -v40, v8, v23
	v_fma_f32 v23, -v41, v9, v23
	v_fma_f32 v23, -v42, v10, v23
	v_fma_f32 v23, -v43, v11, v23
	s_waitcnt lgkmcnt(2)
	v_fma_f32 v23, -v44, v12, v23
	v_fma_f32 v23, -v45, v13, v23
	v_fma_f32 v23, -v46, v14, v23
	v_fma_f32 v23, -v47, v15, v23
	s_waitcnt lgkmcnt(1)
	v_fma_f32 v23, -v48, v16, v23
	v_fma_f32 v23, -v49, v17, v23
	v_fma_f32 v23, -v50, v18, v23
	v_fma_f32 v23, -v51, v19, v23
	s_waitcnt lgkmcnt(0)
	v_fma_f32 v23, -v52, v20, v23
	v_fma_f32 v23, -v53, v21, v23
	v_fma_f32 v23, -v54, v22, v23
	s_lshl_b32 s16, s14, 10
	s_add_u32 s16, s16, 0xe000
	v_lshl_add_u32 v3, v0, 2, s16
	ds_write_b32 v3, v8 offset:0
	ds_write_b32 v3, v9 offset:64
	ds_write_b32 v3, v10 offset:128
	ds_write_b32 v3, v11 offset:192
	ds_write_b32 v3, v12 offset:256
	ds_write_b32 v3, v13 offset:320
	ds_write_b32 v3, v14 offset:384
	ds_write_b32 v3, v15 offset:448
	ds_write_b32 v3, v16 offset:512
	ds_write_b32 v3, v17 offset:576
	ds_write_b32 v3, v18 offset:640
	ds_write_b32 v3, v19 offset:704
	ds_write_b32 v3, v20 offset:768
	ds_write_b32 v3, v21 offset:832
	ds_write_b32 v3, v22 offset:896
	s_waitcnt lgkmcnt(8)
	ds_write_b32 v3, v23 offset:960
	s_mov_b64 exec, s[68:69]
	v_lshlrev_b32_e32 v216, 4, v2
	v_add_u32_e32 v216, 0xc100, v216
	s_cmp_lt_u32 s14, 2
	s_cbranch_scc0 .Lpe_kinit
	s_lshl_b32 s17, s14, 7
	s_add_u32 s17, s17, 0x8000
	v_lshlrev_b32_e32 v255, 10, v2
	v_lshl_add_u32 v255, v0, 1, v255
	v_add_u32_e32 v255, s17, v255
	ds_read_b128 v[122:125], v216 offset:0
	ds_read_u16 v130, v255 offset:0
	ds_read_u16 v131, v255 offset:256
	ds_read_u16 v132, v255 offset:512
	ds_read_u16 v133, v255 offset:768
	ds_read_u16 v220, v255 offset:32
	s_waitcnt lgkmcnt(8)
	ds_read_u16 v221, v255 offset:288
	ds_read_u16 v222, v255 offset:544
	ds_read_u16 v223, v255 offset:800
	s_waitcnt lgkmcnt(7)
	v_lshlrev_b32_e32 v130, 16, v130
	v_mul_f32_e32 v8, v130, v122
	s_waitcnt lgkmcnt(6)
	v_lshlrev_b32_e32 v131, 16, v131
	v_mul_f32_e32 v9, v131, v123
	s_waitcnt lgkmcnt(5)
	v_lshlrev_b32_e32 v132, 16, v132
	v_mul_f32_e32 v10, v132, v124
	s_waitcnt lgkmcnt(4)
	v_lshlrev_b32_e32 v133, 16, v133
	v_mul_f32_e32 v11, v133, v125
	s_waitcnt lgkmcnt(3)
	v_lshlrev_b32_e32 v220, 16, v220
	v_mul_f32_e32 v12, v220, v122
	s_waitcnt lgkmcnt(2)
	v_lshlrev_b32_e32 v221, 16, v221
	v_mul_f32_e32 v13, v221, v123
	s_waitcnt lgkmcnt(1)
	v_lshlrev_b32_e32 v222, 16, v222
	v_mul_f32_e32 v14, v222, v124
	s_waitcnt lgkmcnt(0)
	v_lshlrev_b32_e32 v223, 16, v223
	v_mul_f32_e32 v15, v223, v125
	ds_read_u16 v130, v255 offset:64
	ds_read_u16 v131, v255 offset:320
	ds_read_u16 v132, v255 offset:576
	ds_read_u16 v133, v255 offset:832
	ds_read_u16 v220, v255 offset:96
	ds_read_u16 v221, v255 offset:352
	ds_read_u16 v222, v255 offset:608
	ds_read_u16 v223, v255 offset:864
	s_waitcnt lgkmcnt(7)
	v_lshlrev_b32_e32 v130, 16, v130
	v_mul_f32_e32 v16, v130, v122
	s_waitcnt lgkmcnt(6)
	v_lshlrev_b32_e32 v131, 16, v131
	v_mul_f32_e32 v17, v131, v123
	s_waitcnt lgkmcnt(5)
	v_lshlrev_b32_e32 v132, 16, v132
	v_mul_f32_e32 v18, v132, v124
	s_waitcnt lgkmcnt(4)
	v_lshlrev_b32_e32 v133, 16, v133
	v_mul_f32_e32 v19, v133, v125
	s_waitcnt lgkmcnt(3)
	v_lshlrev_b32_e32 v220, 16, v220
	v_mul_f32_e32 v20, v220, v122
	s_waitcnt lgkmcnt(2)
	v_lshlrev_b32_e32 v221, 16, v221
	v_mul_f32_e32 v21, v221, v123
	s_waitcnt lgkmcnt(1)
	v_lshlrev_b32_e32 v222, 16, v222
	v_mul_f32_e32 v22, v222, v124
	s_waitcnt lgkmcnt(0)
	v_lshlrev_b32_e32 v223, 16, v223
	v_mul_f32_e32 v23, v223, v125
	ds_read_b128 v[122:125], v216 offset:64
	ds_read_u16 v130, v255 offset:4096
	ds_read_u16 v131, v255 offset:4352
	ds_read_u16 v132, v255 offset:4608
	ds_read_u16 v133, v255 offset:4864
	ds_read_u16 v220, v255 offset:4128
	ds_read_u16 v221, v255 offset:4384
	ds_read_u16 v222, v255 offset:4640
	ds_read_u16 v223, v255 offset:4896
	s_waitcnt lgkmcnt(7)
	v_lshlrev_b32_e32 v130, 16, v130
	v_mul_f32_e32 v24, v130, v122
	s_waitcnt lgkmcnt(6)
	v_lshlrev_b32_e32 v131, 16, v131
	v_mul_f32_e32 v25, v131, v123
	s_waitcnt lgkmcnt(5)
	v_lshlrev_b32_e32 v132, 16, v132
	v_mul_f32_e32 v26, v132, v124
	s_waitcnt lgkmcnt(4)
	v_lshlrev_b32_e32 v133, 16, v133
	v_mul_f32_e32 v27, v133, v125
	s_waitcnt lgkmcnt(3)
	v_lshlrev_b32_e32 v220, 16, v220
	v_mul_f32_e32 v28, v220, v122
	s_waitcnt lgkmcnt(2)
	v_lshlrev_b32_e32 v221, 16, v221
	v_mul_f32_e32 v29, v221, v123
	s_waitcnt lgkmcnt(1)
	v_lshlrev_b32_e32 v222, 16, v222
	v_mul_f32_e32 v30, v222, v124
	s_waitcnt lgkmcnt(0)
	v_lshlrev_b32_e32 v223, 16, v223
	v_mul_f32_e32 v31, v223, v125
	ds_read_u16 v130, v255 offset:4160
	ds_read_u16 v131, v255 offset:4416
	ds_read_u16 v132, v255 offset:4672
	ds_read_u16 v133, v255 offset:4928
	ds_read_u16 v220, v255 offset:4192
	ds_read_u16 v221, v255 offset:4448
	ds_read_u16 v222, v255 offset:4704
	ds_read_u16 v223, v255 offset:4960
	s_waitcnt lgkmcnt(7)
	v_lshlrev_b32_e32 v130, 16, v130
	v_mul_f32_e32 v32, v130, v122
	s_waitcnt lgkmcnt(6)
	v_lshlrev_b32_e32 v131, 16, v131
	v_mul_f32_e32 v33, v131, v123
	s_waitcnt lgkmcnt(5)
	v_lshlrev_b32_e32 v132, 16, v132
	v_mul_f32_e32 v34, v132, v124
	s_waitcnt lgkmcnt(4)
	v_lshlrev_b32_e32 v133, 16, v133
	v_mul_f32_e32 v35, v133, v125
	s_waitcnt lgkmcnt(3)
	v_lshlrev_b32_e32 v220, 16, v220
	v_mul_f32_e32 v36, v220, v122
	s_waitcnt lgkmcnt(2)
	v_lshlrev_b32_e32 v221, 16, v221
	v_mul_f32_e32 v37, v221, v123
	s_waitcnt lgkmcnt(1)
	v_lshlrev_b32_e32 v222, 16, v222
	v_mul_f32_e32 v38, v222, v124
	s_waitcnt lgkmcnt(0)
	v_lshlrev_b32_e32 v223, 16, v223
	v_mul_f32_e32 v39, v223, v125
	ds_read_b128 v[122:125], v216 offset:128
	ds_read_u16 v130, v255 offset:8192
	ds_read_u16 v131, v255 offset:8448
	ds_read_u16 v132, v255 offset:8704
	ds_read_u16 v133, v255 offset:8960
	ds_read_u16 v220, v255 offset:8224
	ds_read_u16 v221, v255 offset:8480
	ds_read_u16 v222, v255 offset:8736
	ds_read_u16 v223, v255 offset:8992
	s_waitcnt lgkmcnt(7)
	v_lshlrev_b32_e32 v130, 16, v130
	v_mul_f32_e32 v40, v130, v122
	s_waitcnt lgkmcnt(6)
	v_lshlrev_b32_e32 v131, 16, v131
	v_mul_f32_e32 v41, v131, v123
	s_waitcnt lgkmcnt(5)
	v_lshlrev_b32_e32 v132, 16, v132
	v_mul_f32_e32 v42, v132, v124
	s_waitcnt lgkmcnt(4)
	v_lshlrev_b32_e32 v133, 16, v133
	v_mul_f32_e32 v43, v133, v125
	s_waitcnt lgkmcnt(3)
	v_lshlrev_b32_e32 v220, 16, v220
	v_mul_f32_e32 v44, v220, v122
	s_waitcnt lgkmcnt(2)
	v_lshlrev_b32_e32 v221, 16, v221
	v_mul_f32_e32 v45, v221, v123
	s_waitcnt lgkmcnt(1)
	v_lshlrev_b32_e32 v222, 16, v222
	v_mul_f32_e32 v46, v222, v124
	s_waitcnt lgkmcnt(0)
	v_lshlrev_b32_e32 v223, 16, v223
	v_mul_f32_e32 v47, v223, v125
	ds_read_u16 v130, v255 offset:8256
	ds_read_u16 v131, v255 offset:8512
	ds_read_u16 v132, v255 offset:8768
	ds_read_u16 v133, v255 offset:9024
	ds_read_u16 v220, v255 offset:8288
	ds_read_u16 v221, v255 offset:8544
	ds_read_u16 v222, v255 offset:8800
	ds_read_u16 v223, v255 offset:9056
	s_waitcnt lgkmcnt(7)
	v_lshlrev_b32_e32 v130, 16, v130
	v_mul_f32_e32 v48, v130, v122
	s_waitcnt lgkmcnt(6)
	v_lshlrev_b32_e32 v131, 16, v131
	v_mul_f32_e32 v49, v131, v123
	s_waitcnt lgkmcnt(5)
	v_lshlrev_b32_e32 v132, 16, v132
	v_mul_f32_e32 v50, v132, v124
	s_waitcnt lgkmcnt(4)
	v_lshlrev_b32_e32 v133, 16, v133
	v_mul_f32_e32 v51, v133, v125
	s_waitcnt lgkmcnt(3)
	v_lshlrev_b32_e32 v220, 16, v220
	v_mul_f32_e32 v52, v220, v122
	s_waitcnt lgkmcnt(2)
	v_lshlrev_b32_e32 v221, 16, v221
	v_mul_f32_e32 v53, v221, v123
	s_waitcnt lgkmcnt(1)
	v_lshlrev_b32_e32 v222, 16, v222
	v_mul_f32_e32 v54, v222, v124
	s_waitcnt lgkmcnt(0)
	v_lshlrev_b32_e32 v223, 16, v223
	v_mul_f32_e32 v55, v223, v125
	ds_read_b128 v[122:125], v216 offset:192
	ds_read_u16 v130, v255 offset:12288
	ds_read_u16 v131, v255 offset:12544
	ds_read_u16 v132, v255 offset:12800
	ds_read_u16 v133, v255 offset:13056
	ds_read_u16 v220, v255 offset:12320
	ds_read_u16 v221, v255 offset:12576
	ds_read_u16 v222, v255 offset:12832
	ds_read_u16 v223, v255 offset:13088
	s_waitcnt lgkmcnt(7)
	v_lshlrev_b32_e32 v130, 16, v130
	v_mul_f32_e32 v56, v130, v122
	s_waitcnt lgkmcnt(6)
	v_lshlrev_b32_e32 v131, 16, v131
	v_mul_f32_e32 v57, v131, v123
	s_waitcnt lgkmcnt(5)
	v_lshlrev_b32_e32 v132, 16, v132
	v_mul_f32_e32 v58, v132, v124
	s_waitcnt lgkmcnt(4)
	v_lshlrev_b32_e32 v133, 16, v133
	v_mul_f32_e32 v59, v133, v125
	s_waitcnt lgkmcnt(3)
	v_lshlrev_b32_e32 v220, 16, v220
	v_mul_f32_e32 v60, v220, v122
	s_waitcnt lgkmcnt(2)
	v_lshlrev_b32_e32 v221, 16, v221
	v_mul_f32_e32 v61, v221, v123
	s_waitcnt lgkmcnt(1)
	v_lshlrev_b32_e32 v222, 16, v222
	v_mul_f32_e32 v62, v222, v124
	s_waitcnt lgkmcnt(0)
	v_lshlrev_b32_e32 v223, 16, v223
	v_mul_f32_e32 v63, v223, v125
	ds_read_u16 v130, v255 offset:12352
	ds_read_u16 v131, v255 offset:12608
	ds_read_u16 v132, v255 offset:12864
	ds_read_u16 v133, v255 offset:13120
	ds_read_u16 v220, v255 offset:12384
	ds_read_u16 v221, v255 offset:12640
	ds_read_u16 v222, v255 offset:12896
	ds_read_u16 v223, v255 offset:13152
	s_waitcnt lgkmcnt(7)
	v_lshlrev_b32_e32 v130, 16, v130
	v_mul_f32_e32 v64, v130, v122
	s_waitcnt lgkmcnt(6)
	v_lshlrev_b32_e32 v131, 16, v131
	v_mul_f32_e32 v65, v131, v123
	s_waitcnt lgkmcnt(5)
	v_lshlrev_b32_e32 v132, 16, v132
	v_mul_f32_e32 v66, v132, v124
	s_waitcnt lgkmcnt(4)
	v_lshlrev_b32_e32 v133, 16, v133
	v_mul_f32_e32 v67, v133, v125
	s_waitcnt lgkmcnt(3)
	v_lshlrev_b32_e32 v220, 16, v220
	v_mul_f32_e32 v68, v220, v122
	s_waitcnt lgkmcnt(2)
	v_lshlrev_b32_e32 v221, 16, v221
	v_mul_f32_e32 v69, v221, v123
	s_waitcnt lgkmcnt(1)
	v_lshlrev_b32_e32 v222, 16, v222
	v_mul_f32_e32 v70, v222, v124
	s_waitcnt lgkmcnt(0)
	v_lshlrev_b32_e32 v223, 16, v223
	v_mul_f32_e32 v71, v223, v125
	s_branch .Lpe_init_done
.Lpe_kinit:
	s_sub_u32 s17, s14, 2
	s_lshl_b32 s17, s17, 3
	v_lshrrev_b32_e32 v3, 3, v0
	v_add_u32_e32 v3, s17, v3
	v_lshlrev_b32_e32 v255, 2, v2
	v_xor_b32_e32 v3, v3, v255
	v_and_b32_e32 v255, 7, v0
	v_lshlrev_b32_e32 v255, 1, v255
	v_lshl_add_u32 v255, v2, 10, v255
	v_xor_b32_e32 v217, 0, v3
	v_lshl_add_u32 v217, v217, 4, v255
	v_xor_b32_e32 v218, 1, v3
	v_lshl_add_u32 v218, v218, 4, v255
	v_xor_b32_e32 v230, 2, v3
	v_lshl_add_u32 v230, v230, 4, v255
	v_xor_b32_e32 v231, 3, v3
	v_lshl_add_u32 v231, v231, 4, v255
	v_xor_b32_e32 v248, 4, v3
	v_lshl_add_u32 v248, v248, 4, v255
	v_xor_b32_e32 v249, 5, v3
	v_lshl_add_u32 v249, v249, 4, v255
	v_xor_b32_e32 v253, 6, v3
	v_lshl_add_u32 v253, v253, 4, v255
	v_xor_b32_e32 v254, 7, v3
	v_lshl_add_u32 v254, v254, 4, v255
	ds_read_b128 v[122:125], v216 offset:0
	ds_read_b128 v[126:129], v216 offset:256
	ds_read_u16 v130, v217 offset:0
	ds_read_u16 v131, v218 offset:256
	ds_read_u16 v132, v230 offset:512
	ds_read_u16 v133, v231 offset:768
	s_waitcnt lgkmcnt(8)
	ds_read_u16 v220, v230 offset:0
	ds_read_u16 v221, v231 offset:256
	ds_read_u16 v222, v217 offset:512
	ds_read_u16 v223, v218 offset:768
	s_waitcnt lgkmcnt(7)
	v_lshlrev_b32_e32 v130, 16, v130
	v_mul_f32_e32 v130, v130, v122
	v_mul_f32_e32 v8, v130, v126
	s_waitcnt lgkmcnt(6)
	v_lshlrev_b32_e32 v131, 16, v131
	v_mul_f32_e32 v131, v131, v123
	v_mul_f32_e32 v9, v131, v127
	s_waitcnt lgkmcnt(5)
	v_lshlrev_b32_e32 v132, 16, v132
	v_mul_f32_e32 v132, v132, v124
	v_mul_f32_e32 v10, v132, v128
	s_waitcnt lgkmcnt(4)
	v_lshlrev_b32_e32 v133, 16, v133
	v_mul_f32_e32 v133, v133, v125
	v_mul_f32_e32 v11, v133, v129
	s_waitcnt lgkmcnt(3)
	v_lshlrev_b32_e32 v220, 16, v220
	v_mul_f32_e32 v220, v220, v122
	v_mul_f32_e32 v12, v220, v126
	s_waitcnt lgkmcnt(2)
	v_lshlrev_b32_e32 v221, 16, v221
	v_mul_f32_e32 v221, v221, v123
	v_mul_f32_e32 v13, v221, v127
	s_waitcnt lgkmcnt(1)
	v_lshlrev_b32_e32 v222, 16, v222
	v_mul_f32_e32 v222, v222, v124
	v_mul_f32_e32 v14, v222, v128
	s_waitcnt lgkmcnt(0)
	v_lshlrev_b32_e32 v223, 16, v223
	v_mul_f32_e32 v223, v223, v125
	v_mul_f32_e32 v15, v223, v129
	ds_read_u16 v130, v248 offset:0
	ds_read_u16 v131, v249 offset:256
	ds_read_u16 v132, v253 offset:512
	ds_read_u16 v133, v254 offset:768
	ds_read_u16 v220, v253 offset:0
	ds_read_u16 v221, v254 offset:256
	ds_read_u16 v222, v248 offset:512
	ds_read_u16 v223, v249 offset:768
	s_waitcnt lgkmcnt(7)
	v_lshlrev_b32_e32 v130, 16, v130
	v_mul_f32_e32 v130, v130, v122
	v_mul_f32_e32 v16, v130, v126
	s_waitcnt lgkmcnt(6)
	v_lshlrev_b32_e32 v131, 16, v131
	v_mul_f32_e32 v131, v131, v123
	v_mul_f32_e32 v17, v131, v127
	s_waitcnt lgkmcnt(5)
	v_lshlrev_b32_e32 v132, 16, v132
	v_mul_f32_e32 v132, v132, v124
	v_mul_f32_e32 v18, v132, v128
	s_waitcnt lgkmcnt(4)
	v_lshlrev_b32_e32 v133, 16, v133
	v_mul_f32_e32 v133, v133, v125
	v_mul_f32_e32 v19, v133, v129
	s_waitcnt lgkmcnt(3)
	v_lshlrev_b32_e32 v220, 16, v220
	v_mul_f32_e32 v220, v220, v122
	v_mul_f32_e32 v20, v220, v126
	s_waitcnt lgkmcnt(2)
	v_lshlrev_b32_e32 v221, 16, v221
	v_mul_f32_e32 v221, v221, v123
	v_mul_f32_e32 v21, v221, v127
	s_waitcnt lgkmcnt(1)
	v_lshlrev_b32_e32 v222, 16, v222
	v_mul_f32_e32 v222, v222, v124
	v_mul_f32_e32 v22, v222, v128
	s_waitcnt lgkmcnt(0)
	v_lshlrev_b32_e32 v223, 16, v223
	v_mul_f32_e32 v223, v223, v125
	v_mul_f32_e32 v23, v223, v129
	ds_read_b128 v[122:125], v216 offset:64
	ds_read_b128 v[126:129], v216 offset:320
	ds_read_u16 v130, v217 offset:4096
	ds_read_u16 v131, v218 offset:4352
	ds_read_u16 v132, v230 offset:4608
	ds_read_u16 v133, v231 offset:4864
	ds_read_u16 v220, v230 offset:4096
	ds_read_u16 v221, v231 offset:4352
	ds_read_u16 v222, v217 offset:4608
	ds_read_u16 v223, v218 offset:4864
	s_waitcnt lgkmcnt(7)
	v_lshlrev_b32_e32 v130, 16, v130
	v_mul_f32_e32 v130, v130, v122
	v_mul_f32_e32 v24, v130, v126
	s_waitcnt lgkmcnt(6)
	v_lshlrev_b32_e32 v131, 16, v131
	v_mul_f32_e32 v131, v131, v123
	v_mul_f32_e32 v25, v131, v127
	s_waitcnt lgkmcnt(5)
	v_lshlrev_b32_e32 v132, 16, v132
	v_mul_f32_e32 v132, v132, v124
	v_mul_f32_e32 v26, v132, v128
	s_waitcnt lgkmcnt(4)
	v_lshlrev_b32_e32 v133, 16, v133
	v_mul_f32_e32 v133, v133, v125
	v_mul_f32_e32 v27, v133, v129
	s_waitcnt lgkmcnt(3)
	v_lshlrev_b32_e32 v220, 16, v220
	v_mul_f32_e32 v220, v220, v122
	v_mul_f32_e32 v28, v220, v126
	s_waitcnt lgkmcnt(2)
	v_lshlrev_b32_e32 v221, 16, v221
	v_mul_f32_e32 v221, v221, v123
	v_mul_f32_e32 v29, v221, v127
	s_waitcnt lgkmcnt(1)
	v_lshlrev_b32_e32 v222, 16, v222
	v_mul_f32_e32 v222, v222, v124
	v_mul_f32_e32 v30, v222, v128
	s_waitcnt lgkmcnt(0)
	v_lshlrev_b32_e32 v223, 16, v223
	v_mul_f32_e32 v223, v223, v125
	v_mul_f32_e32 v31, v223, v129
	ds_read_u16 v130, v248 offset:4096
	ds_read_u16 v131, v249 offset:4352
	ds_read_u16 v132, v253 offset:4608
	ds_read_u16 v133, v254 offset:4864
	ds_read_u16 v220, v253 offset:4096
	ds_read_u16 v221, v254 offset:4352
	ds_read_u16 v222, v248 offset:4608
	ds_read_u16 v223, v249 offset:4864
	s_waitcnt lgkmcnt(7)
	v_lshlrev_b32_e32 v130, 16, v130
	v_mul_f32_e32 v130, v130, v122
	v_mul_f32_e32 v32, v130, v126
	s_waitcnt lgkmcnt(6)
	v_lshlrev_b32_e32 v131, 16, v131
	v_mul_f32_e32 v131, v131, v123
	v_mul_f32_e32 v33, v131, v127
	s_waitcnt lgkmcnt(5)
	v_lshlrev_b32_e32 v132, 16, v132
	v_mul_f32_e32 v132, v132, v124
	v_mul_f32_e32 v34, v132, v128
	s_waitcnt lgkmcnt(4)
	v_lshlrev_b32_e32 v133, 16, v133
	v_mul_f32_e32 v133, v133, v125
	v_mul_f32_e32 v35, v133, v129
	s_waitcnt lgkmcnt(3)
	v_lshlrev_b32_e32 v220, 16, v220
	v_mul_f32_e32 v220, v220, v122
	v_mul_f32_e32 v36, v220, v126
	s_waitcnt lgkmcnt(2)
	v_lshlrev_b32_e32 v221, 16, v221
	v_mul_f32_e32 v221, v221, v123
	v_mul_f32_e32 v37, v221, v127
	s_waitcnt lgkmcnt(1)
	v_lshlrev_b32_e32 v222, 16, v222
	v_mul_f32_e32 v222, v222, v124
	v_mul_f32_e32 v38, v222, v128
	s_waitcnt lgkmcnt(0)
	v_lshlrev_b32_e32 v223, 16, v223
	v_mul_f32_e32 v223, v223, v125
	v_mul_f32_e32 v39, v223, v129
	ds_read_b128 v[122:125], v216 offset:128
	ds_read_b128 v[126:129], v216 offset:384
	ds_read_u16 v130, v217 offset:8192
	ds_read_u16 v131, v218 offset:8448
	ds_read_u16 v132, v230 offset:8704
	ds_read_u16 v133, v231 offset:8960
	ds_read_u16 v220, v230 offset:8192
	ds_read_u16 v221, v231 offset:8448
	ds_read_u16 v222, v217 offset:8704
	ds_read_u16 v223, v218 offset:8960
	s_waitcnt lgkmcnt(7)
	v_lshlrev_b32_e32 v130, 16, v130
	v_mul_f32_e32 v130, v130, v122
	v_mul_f32_e32 v40, v130, v126
	s_waitcnt lgkmcnt(6)
	v_lshlrev_b32_e32 v131, 16, v131
	v_mul_f32_e32 v131, v131, v123
	v_mul_f32_e32 v41, v131, v127
	s_waitcnt lgkmcnt(5)
	v_lshlrev_b32_e32 v132, 16, v132
	v_mul_f32_e32 v132, v132, v124
	v_mul_f32_e32 v42, v132, v128
	s_waitcnt lgkmcnt(4)
	v_lshlrev_b32_e32 v133, 16, v133
	v_mul_f32_e32 v133, v133, v125
	v_mul_f32_e32 v43, v133, v129
	s_waitcnt lgkmcnt(3)
	v_lshlrev_b32_e32 v220, 16, v220
	v_mul_f32_e32 v220, v220, v122
	v_mul_f32_e32 v44, v220, v126
	s_waitcnt lgkmcnt(2)
	v_lshlrev_b32_e32 v221, 16, v221
	v_mul_f32_e32 v221, v221, v123
	v_mul_f32_e32 v45, v221, v127
	s_waitcnt lgkmcnt(1)
	v_lshlrev_b32_e32 v222, 16, v222
	v_mul_f32_e32 v222, v222, v124
	v_mul_f32_e32 v46, v222, v128
	s_waitcnt lgkmcnt(0)
	v_lshlrev_b32_e32 v223, 16, v223
	v_mul_f32_e32 v223, v223, v125
	v_mul_f32_e32 v47, v223, v129
	ds_read_u16 v130, v248 offset:8192
	ds_read_u16 v131, v249 offset:8448
	ds_read_u16 v132, v253 offset:8704
	ds_read_u16 v133, v254 offset:8960
	ds_read_u16 v220, v253 offset:8192
	ds_read_u16 v221, v254 offset:8448
	ds_read_u16 v222, v248 offset:8704
	ds_read_u16 v223, v249 offset:8960
	s_waitcnt lgkmcnt(7)
	v_lshlrev_b32_e32 v130, 16, v130
	v_mul_f32_e32 v130, v130, v122
	v_mul_f32_e32 v48, v130, v126
	s_waitcnt lgkmcnt(6)
	v_lshlrev_b32_e32 v131, 16, v131
	v_mul_f32_e32 v131, v131, v123
	v_mul_f32_e32 v49, v131, v127
	s_waitcnt lgkmcnt(5)
	v_lshlrev_b32_e32 v132, 16, v132
	v_mul_f32_e32 v132, v132, v124
	v_mul_f32_e32 v50, v132, v128
	s_waitcnt lgkmcnt(4)
	v_lshlrev_b32_e32 v133, 16, v133
	v_mul_f32_e32 v133, v133, v125
	v_mul_f32_e32 v51, v133, v129
	s_waitcnt lgkmcnt(3)
	v_lshlrev_b32_e32 v220, 16, v220
	v_mul_f32_e32 v220, v220, v122
	v_mul_f32_e32 v52, v220, v126
	s_waitcnt lgkmcnt(2)
	v_lshlrev_b32_e32 v221, 16, v221
	v_mul_f32_e32 v221, v221, v123
	v_mul_f32_e32 v53, v221, v127
	s_waitcnt lgkmcnt(1)
	v_lshlrev_b32_e32 v222, 16, v222
	v_mul_f32_e32 v222, v222, v124
	v_mul_f32_e32 v54, v222, v128
	s_waitcnt lgkmcnt(0)
	v_lshlrev_b32_e32 v223, 16, v223
	v_mul_f32_e32 v223, v223, v125
	v_mul_f32_e32 v55, v223, v129
	ds_read_b128 v[122:125], v216 offset:192
	ds_read_b128 v[126:129], v216 offset:448
	ds_read_u16 v130, v217 offset:12288
	ds_read_u16 v131, v218 offset:12544
	ds_read_u16 v132, v230 offset:12800
	ds_read_u16 v133, v231 offset:13056
	ds_read_u16 v220, v230 offset:12288
	ds_read_u16 v221, v231 offset:12544
	ds_read_u16 v222, v217 offset:12800
	ds_read_u16 v223, v218 offset:13056
	s_waitcnt lgkmcnt(7)
	v_lshlrev_b32_e32 v130, 16, v130
	v_mul_f32_e32 v130, v130, v122
	v_mul_f32_e32 v56, v130, v126
	s_waitcnt lgkmcnt(6)
	v_lshlrev_b32_e32 v131, 16, v131
	v_mul_f32_e32 v131, v131, v123
	v_mul_f32_e32 v57, v131, v127
	s_waitcnt lgkmcnt(5)
	v_lshlrev_b32_e32 v132, 16, v132
	v_mul_f32_e32 v132, v132, v124
	v_mul_f32_e32 v58, v132, v128
	s_waitcnt lgkmcnt(4)
	v_lshlrev_b32_e32 v133, 16, v133
	v_mul_f32_e32 v133, v133, v125
	v_mul_f32_e32 v59, v133, v129
	s_waitcnt lgkmcnt(3)
	v_lshlrev_b32_e32 v220, 16, v220
	v_mul_f32_e32 v220, v220, v122
	v_mul_f32_e32 v60, v220, v126
	s_waitcnt lgkmcnt(2)
	v_lshlrev_b32_e32 v221, 16, v221
	v_mul_f32_e32 v221, v221, v123
	v_mul_f32_e32 v61, v221, v127
	s_waitcnt lgkmcnt(1)
	v_lshlrev_b32_e32 v222, 16, v222
	v_mul_f32_e32 v222, v222, v124
	v_mul_f32_e32 v62, v222, v128
	s_waitcnt lgkmcnt(0)
	v_lshlrev_b32_e32 v223, 16, v223
	v_mul_f32_e32 v223, v223, v125
	v_mul_f32_e32 v63, v223, v129
	ds_read_u16 v130, v248 offset:12288
	ds_read_u16 v131, v249 offset:12544
	ds_read_u16 v132, v253 offset:12800
	ds_read_u16 v133, v254 offset:13056
	ds_read_u16 v220, v253 offset:12288
	ds_read_u16 v221, v254 offset:12544
	ds_read_u16 v222, v248 offset:12800
	ds_read_u16 v223, v249 offset:13056
	s_waitcnt lgkmcnt(7)
	v_lshlrev_b32_e32 v130, 16, v130
	v_mul_f32_e32 v130, v130, v122
	v_mul_f32_e32 v64, v130, v126
	s_waitcnt lgkmcnt(6)
	v_lshlrev_b32_e32 v131, 16, v131
	v_mul_f32_e32 v131, v131, v123
	v_mul_f32_e32 v65, v131, v127
	s_waitcnt lgkmcnt(5)
	v_lshlrev_b32_e32 v132, 16, v132
	v_mul_f32_e32 v132, v132, v124
	v_mul_f32_e32 v66, v132, v128
	s_waitcnt lgkmcnt(4)
	v_lshlrev_b32_e32 v133, 16, v133
	v_mul_f32_e32 v133, v133, v125
	v_mul_f32_e32 v67, v133, v129
	s_waitcnt lgkmcnt(3)
	v_lshlrev_b32_e32 v220, 16, v220
	v_mul_f32_e32 v220, v220, v122
	v_mul_f32_e32 v68, v220, v126
	s_waitcnt lgkmcnt(2)
	v_lshlrev_b32_e32 v221, 16, v221
	v_mul_f32_e32 v221, v221, v123
	v_mul_f32_e32 v69, v221, v127
	s_waitcnt lgkmcnt(1)
	v_lshlrev_b32_e32 v222, 16, v222
	v_mul_f32_e32 v222, v222, v124
	v_mul_f32_e32 v70, v222, v128
	s_waitcnt lgkmcnt(0)
	v_lshlrev_b32_e32 v223, 16, v223
	v_mul_f32_e32 v223, v223, v125
	v_mul_f32_e32 v71, v223, v129
.Lpe_init_done:
	s_waitcnt lgkmcnt(0)
	s_barrier
	v_lshlrev_b32_e32 v134, 6, v0
	v_lshl_add_u32 v134, v2, 2, v134
	v_lshlrev_b32_e32 v134, 2, v134
	v_add_u32_e32 v134, 0x4000, v134
	v_lshlrev_b32_e32 v135, 6, v0
	v_lshl_add_u32 v135, v2, 4, v135
	v_add_u32_e32 v135, 0xe000, v135
	v_mov_b32_e32 v122, v8
	v_mov_b32_e32 v123, v9
	v_mov_b32_e32 v124, v10
	v_mov_b32_e32 v125, v11
	v_mov_b32_e32 v126, v12
	v_mov_b32_e32 v127, v13
	v_mov_b32_e32 v128, v14
	v_mov_b32_e32 v129, v15
	v_mov_b32_e32 v130, v16
	v_mov_b32_e32 v131, v17
	v_mov_b32_e32 v132, v18
	v_mov_b32_e32 v133, v19
	v_mov_b32_e32 v220, v20
	v_mov_b32_e32 v221, v21
	v_mov_b32_e32 v222, v22
	v_mov_b32_e32 v223, v23
	ds_read_b128 v[224:227], v135 offset:0
	s_waitcnt lgkmcnt(0)
	s_nop 1
	v_mfma_f32_16x16x4_f32 v[8:11], v224, v122, 0
	v_mfma_f32_16x16x4_f32 v[12:15], v224, v126, 0
	v_mfma_f32_16x16x4_f32 v[16:19], v224, v130, 0
	v_mfma_f32_16x16x4_f32 v[20:23], v224, v220, 0
	v_mfma_f32_16x16x4_f32 v[8:11], v225, v123, v[8:11]
	v_mfma_f32_16x16x4_f32 v[12:15], v225, v127, v[12:15]
	v_mfma_f32_16x16x4_f32 v[16:19], v225, v131, v[16:19]
	v_mfma_f32_16x16x4_f32 v[20:23], v225, v221, v[20:23]
	v_mfma_f32_16x16x4_f32 v[8:11], v226, v124, v[8:11]
	v_mfma_f32_16x16x4_f32 v[12:15], v226, v128, v[12:15]
	v_mfma_f32_16x16x4_f32 v[16:19], v226, v132, v[16:19]
	v_mfma_f32_16x16x4_f32 v[20:23], v226, v222, v[20:23]
	v_mfma_f32_16x16x4_f32 v[8:11], v227, v125, v[8:11]
	v_mfma_f32_16x16x4_f32 v[12:15], v227, v129, v[12:15]
	v_mfma_f32_16x16x4_f32 v[16:19], v227, v133, v[16:19]
	v_mfma_f32_16x16x4_f32 v[20:23], v227, v223, v[20:23]
	s_nop 7
	s_nop 7
	s_nop 7
	ds_read_b128 v[224:227], v134 offset:4096
	s_waitcnt lgkmcnt(0)
	v_mfma_f32_16x16x4_f32 v[122:125], v224, v8, 0
	v_mfma_f32_16x16x4_f32 v[126:129], v224, v12, 0
	v_mfma_f32_16x16x4_f32 v[130:133], v224, v16, 0
	v_mfma_f32_16x16x4_f32 v[220:223], v224, v20, 0
	v_mfma_f32_16x16x4_f32 v[122:125], v225, v9, v[122:125]
	v_mfma_f32_16x16x4_f32 v[126:129], v225, v13, v[126:129]
	v_mfma_f32_16x16x4_f32 v[130:133], v225, v17, v[130:133]
	v_mfma_f32_16x16x4_f32 v[220:223], v225, v21, v[220:223]
	v_mfma_f32_16x16x4_f32 v[122:125], v226, v10, v[122:125]
	v_mfma_f32_16x16x4_f32 v[126:129], v226, v14, v[126:129]
	v_mfma_f32_16x16x4_f32 v[130:133], v226, v18, v[130:133]
	v_mfma_f32_16x16x4_f32 v[220:223], v226, v22, v[220:223]
	v_mfma_f32_16x16x4_f32 v[122:125], v227, v11, v[122:125]
	v_mfma_f32_16x16x4_f32 v[126:129], v227, v15, v[126:129]
	v_mfma_f32_16x16x4_f32 v[130:133], v227, v19, v[130:133]
	v_mfma_f32_16x16x4_f32 v[220:223], v227, v23, v[220:223]
	ds_read_b128 v[224:227], v135 offset:1024
	s_nop 7
	s_nop 7
	s_nop 7
	v_sub_f32_e32 v122, v24, v122
	v_sub_f32_e32 v123, v25, v123
	v_sub_f32_e32 v124, v26, v124
	v_sub_f32_e32 v125, v27, v125
	v_sub_f32_e32 v126, v28, v126
	v_sub_f32_e32 v127, v29, v127
	v_sub_f32_e32 v128, v30, v128
	v_sub_f32_e32 v129, v31, v129
	v_sub_f32_e32 v130, v32, v130
	v_sub_f32_e32 v131, v33, v131
	v_sub_f32_e32 v132, v34, v132
	v_sub_f32_e32 v133, v35, v133
	v_sub_f32_e32 v220, v36, v220
	v_sub_f32_e32 v221, v37, v221
	v_sub_f32_e32 v222, v38, v222
	v_sub_f32_e32 v223, v39, v223
	s_waitcnt lgkmcnt(0)
	s_nop 1
	v_mfma_f32_16x16x4_f32 v[24:27], v224, v122, 0
	v_mfma_f32_16x16x4_f32 v[28:31], v224, v126, 0
	v_mfma_f32_16x16x4_f32 v[32:35], v224, v130, 0
	v_mfma_f32_16x16x4_f32 v[36:39], v224, v220, 0
	v_mfma_f32_16x16x4_f32 v[24:27], v225, v123, v[24:27]
	v_mfma_f32_16x16x4_f32 v[28:31], v225, v127, v[28:31]
	v_mfma_f32_16x16x4_f32 v[32:35], v225, v131, v[32:35]
	v_mfma_f32_16x16x4_f32 v[36:39], v225, v221, v[36:39]
	v_mfma_f32_16x16x4_f32 v[24:27], v226, v124, v[24:27]
	v_mfma_f32_16x16x4_f32 v[28:31], v226, v128, v[28:31]
	v_mfma_f32_16x16x4_f32 v[32:35], v226, v132, v[32:35]
	v_mfma_f32_16x16x4_f32 v[36:39], v226, v222, v[36:39]
	v_mfma_f32_16x16x4_f32 v[24:27], v227, v125, v[24:27]
	v_mfma_f32_16x16x4_f32 v[28:31], v227, v129, v[28:31]
	v_mfma_f32_16x16x4_f32 v[32:35], v227, v133, v[32:35]
	v_mfma_f32_16x16x4_f32 v[36:39], v227, v223, v[36:39]
	s_nop 7
	s_nop 7
	s_nop 7
	ds_read_b128 v[224:227], v134 offset:8192
	s_waitcnt lgkmcnt(0)
	v_mfma_f32_16x16x4_f32 v[122:125], v224, v8, 0
	v_mfma_f32_16x16x4_f32 v[126:129], v224, v12, 0
	v_mfma_f32_16x16x4_f32 v[130:133], v224, v16, 0
	v_mfma_f32_16x16x4_f32 v[220:223], v224, v20, 0
	v_mfma_f32_16x16x4_f32 v[122:125], v225, v9, v[122:125]
	v_mfma_f32_16x16x4_f32 v[126:129], v225, v13, v[126:129]
	v_mfma_f32_16x16x4_f32 v[130:133], v225, v17, v[130:133]
	v_mfma_f32_16x16x4_f32 v[220:223], v225, v21, v[220:223]
	v_mfma_f32_16x16x4_f32 v[122:125], v226, v10, v[122:125]
	v_mfma_f32_16x16x4_f32 v[126:129], v226, v14, v[126:129]
	v_mfma_f32_16x16x4_f32 v[130:133], v226, v18, v[130:133]
	v_mfma_f32_16x16x4_f32 v[220:223], v226, v22, v[220:223]
	v_mfma_f32_16x16x4_f32 v[122:125], v227, v11, v[122:125]
	v_mfma_f32_16x16x4_f32 v[126:129], v227, v15, v[126:129]
	v_mfma_f32_16x16x4_f32 v[130:133], v227, v19, v[130:133]
	v_mfma_f32_16x16x4_f32 v[220:223], v227, v23, v[220:223]
	ds_read_b128 v[224:227], v134 offset:8256
	s_waitcnt lgkmcnt(0)
	v_mfma_f32_16x16x4_f32 v[122:125], v224, v24, v[122:125]
	v_mfma_f32_16x16x4_f32 v[126:129], v224, v28, v[126:129]
	v_mfma_f32_16x16x4_f32 v[130:133], v224, v32, v[130:133]
	v_mfma_f32_16x16x4_f32 v[220:223], v224, v36, v[220:223]
	v_mfma_f32_16x16x4_f32 v[122:125], v225, v25, v[122:125]
	v_mfma_f32_16x16x4_f32 v[126:129], v225, v29, v[126:129]
	v_mfma_f32_16x16x4_f32 v[130:133], v225, v33, v[130:133]
	v_mfma_f32_16x16x4_f32 v[220:223], v225, v37, v[220:223]
	v_mfma_f32_16x16x4_f32 v[122:125], v226, v26, v[122:125]
	v_mfma_f32_16x16x4_f32 v[126:129], v226, v30, v[126:129]
	v_mfma_f32_16x16x4_f32 v[130:133], v226, v34, v[130:133]
	v_mfma_f32_16x16x4_f32 v[220:223], v226, v38, v[220:223]
	v_mfma_f32_16x16x4_f32 v[122:125], v227, v27, v[122:125]
	v_mfma_f32_16x16x4_f32 v[126:129], v227, v31, v[126:129]
	v_mfma_f32_16x16x4_f32 v[130:133], v227, v35, v[130:133]
	v_mfma_f32_16x16x4_f32 v[220:223], v227, v39, v[220:223]
	ds_read_b128 v[224:227], v135 offset:2048
	s_nop 7
	s_nop 7
	s_nop 7
	v_sub_f32_e32 v122, v40, v122
	v_sub_f32_e32 v123, v41, v123
	v_sub_f32_e32 v124, v42, v124
	v_sub_f32_e32 v125, v43, v125
	v_sub_f32_e32 v126, v44, v126
	v_sub_f32_e32 v127, v45, v127
	v_sub_f32_e32 v128, v46, v128
	v_sub_f32_e32 v129, v47, v129
	v_sub_f32_e32 v130, v48, v130
	v_sub_f32_e32 v131, v49, v131
	v_sub_f32_e32 v132, v50, v132
	v_sub_f32_e32 v133, v51, v133
	v_sub_f32_e32 v220, v52, v220
	v_sub_f32_e32 v221, v53, v221
	v_sub_f32_e32 v222, v54, v222
	v_sub_f32_e32 v223, v55, v223
	s_waitcnt lgkmcnt(0)
	s_nop 1
	v_mfma_f32_16x16x4_f32 v[40:43], v224, v122, 0
	v_mfma_f32_16x16x4_f32 v[44:47], v224, v126, 0
	v_mfma_f32_16x16x4_f32 v[48:51], v224, v130, 0
	v_mfma_f32_16x16x4_f32 v[52:55], v224, v220, 0
	v_mfma_f32_16x16x4_f32 v[40:43], v225, v123, v[40:43]
	v_mfma_f32_16x16x4_f32 v[44:47], v225, v127, v[44:47]
	v_mfma_f32_16x16x4_f32 v[48:51], v225, v131, v[48:51]
	v_mfma_f32_16x16x4_f32 v[52:55], v225, v221, v[52:55]
	v_mfma_f32_16x16x4_f32 v[40:43], v226, v124, v[40:43]
	v_mfma_f32_16x16x4_f32 v[44:47], v226, v128, v[44:47]
	v_mfma_f32_16x16x4_f32 v[48:51], v226, v132, v[48:51]
	v_mfma_f32_16x16x4_f32 v[52:55], v226, v222, v[52:55]
	v_mfma_f32_16x16x4_f32 v[40:43], v227, v125, v[40:43]
	v_mfma_f32_16x16x4_f32 v[44:47], v227, v129, v[44:47]
	v_mfma_f32_16x16x4_f32 v[48:51], v227, v133, v[48:51]
	v_mfma_f32_16x16x4_f32 v[52:55], v227, v223, v[52:55]
	s_nop 7
	s_nop 7
	s_nop 7
	ds_read_b128 v[224:227], v134 offset:12288
	s_waitcnt lgkmcnt(0)
	v_mfma_f32_16x16x4_f32 v[122:125], v224, v8, 0
	v_mfma_f32_16x16x4_f32 v[126:129], v224, v12, 0
	v_mfma_f32_16x16x4_f32 v[130:133], v224, v16, 0
	v_mfma_f32_16x16x4_f32 v[220:223], v224, v20, 0
	v_mfma_f32_16x16x4_f32 v[122:125], v225, v9, v[122:125]
	v_mfma_f32_16x16x4_f32 v[126:129], v225, v13, v[126:129]
	v_mfma_f32_16x16x4_f32 v[130:133], v225, v17, v[130:133]
	v_mfma_f32_16x16x4_f32 v[220:223], v225, v21, v[220:223]
	v_mfma_f32_16x16x4_f32 v[122:125], v226, v10, v[122:125]
	v_mfma_f32_16x16x4_f32 v[126:129], v226, v14, v[126:129]
	v_mfma_f32_16x16x4_f32 v[130:133], v226, v18, v[130:133]
	v_mfma_f32_16x16x4_f32 v[220:223], v226, v22, v[220:223]
	v_mfma_f32_16x16x4_f32 v[122:125], v227, v11, v[122:125]
	v_mfma_f32_16x16x4_f32 v[126:129], v227, v15, v[126:129]
	v_mfma_f32_16x16x4_f32 v[130:133], v227, v19, v[130:133]
	v_mfma_f32_16x16x4_f32 v[220:223], v227, v23, v[220:223]
	ds_read_b128 v[224:227], v134 offset:12352
	s_waitcnt lgkmcnt(0)
	v_mfma_f32_16x16x4_f32 v[122:125], v224, v24, v[122:125]
	v_mfma_f32_16x16x4_f32 v[126:129], v224, v28, v[126:129]
	v_mfma_f32_16x16x4_f32 v[130:133], v224, v32, v[130:133]
	v_mfma_f32_16x16x4_f32 v[220:223], v224, v36, v[220:223]
	v_mfma_f32_16x16x4_f32 v[122:125], v225, v25, v[122:125]
	v_mfma_f32_16x16x4_f32 v[126:129], v225, v29, v[126:129]
	v_mfma_f32_16x16x4_f32 v[130:133], v225, v33, v[130:133]
	v_mfma_f32_16x16x4_f32 v[220:223], v225, v37, v[220:223]
	v_mfma_f32_16x16x4_f32 v[122:125], v226, v26, v[122:125]
	v_mfma_f32_16x16x4_f32 v[126:129], v226, v30, v[126:129]
	v_mfma_f32_16x16x4_f32 v[130:133], v226, v34, v[130:133]
	v_mfma_f32_16x16x4_f32 v[220:223], v226, v38, v[220:223]
	v_mfma_f32_16x16x4_f32 v[122:125], v227, v27, v[122:125]
	v_mfma_f32_16x16x4_f32 v[126:129], v227, v31, v[126:129]
	v_mfma_f32_16x16x4_f32 v[130:133], v227, v35, v[130:133]
	v_mfma_f32_16x16x4_f32 v[220:223], v227, v39, v[220:223]
	ds_read_b128 v[224:227], v134 offset:12416
	s_waitcnt lgkmcnt(0)
	v_mfma_f32_16x16x4_f32 v[122:125], v224, v40, v[122:125]
	v_mfma_f32_16x16x4_f32 v[126:129], v224, v44, v[126:129]
	v_mfma_f32_16x16x4_f32 v[130:133], v224, v48, v[130:133]
	v_mfma_f32_16x16x4_f32 v[220:223], v224, v52, v[220:223]
	v_mfma_f32_16x16x4_f32 v[122:125], v225, v41, v[122:125]
	v_mfma_f32_16x16x4_f32 v[126:129], v225, v45, v[126:129]
	v_mfma_f32_16x16x4_f32 v[130:133], v225, v49, v[130:133]
	v_mfma_f32_16x16x4_f32 v[220:223], v225, v53, v[220:223]
	v_mfma_f32_16x16x4_f32 v[122:125], v226, v42, v[122:125]
	v_mfma_f32_16x16x4_f32 v[126:129], v226, v46, v[126:129]
	v_mfma_f32_16x16x4_f32 v[130:133], v226, v50, v[130:133]
	v_mfma_f32_16x16x4_f32 v[220:223], v226, v54, v[220:223]
	v_mfma_f32_16x16x4_f32 v[122:125], v227, v43, v[122:125]
	v_mfma_f32_16x16x4_f32 v[126:129], v227, v47, v[126:129]
	v_mfma_f32_16x16x4_f32 v[130:133], v227, v51, v[130:133]
	v_mfma_f32_16x16x4_f32 v[220:223], v227, v55, v[220:223]
	ds_read_b128 v[224:227], v135 offset:3072
	s_nop 7
	s_nop 7
	s_nop 7
	v_sub_f32_e32 v122, v56, v122
	v_sub_f32_e32 v123, v57, v123
	v_sub_f32_e32 v124, v58, v124
	v_sub_f32_e32 v125, v59, v125
	v_sub_f32_e32 v126, v60, v126
	v_sub_f32_e32 v127, v61, v127
	v_sub_f32_e32 v128, v62, v128
	v_sub_f32_e32 v129, v63, v129
	v_sub_f32_e32 v130, v64, v130
	v_sub_f32_e32 v131, v65, v131
	v_sub_f32_e32 v132, v66, v132
	v_sub_f32_e32 v133, v67, v133
	v_sub_f32_e32 v220, v68, v220
	v_sub_f32_e32 v221, v69, v221
	v_sub_f32_e32 v222, v70, v222
	v_sub_f32_e32 v223, v71, v223
	s_waitcnt lgkmcnt(0)
	s_nop 1
	v_mfma_f32_16x16x4_f32 v[56:59], v224, v122, 0
	v_mfma_f32_16x16x4_f32 v[60:63], v224, v126, 0
	v_mfma_f32_16x16x4_f32 v[64:67], v224, v130, 0
	v_mfma_f32_16x16x4_f32 v[68:71], v224, v220, 0
	v_mfma_f32_16x16x4_f32 v[56:59], v225, v123, v[56:59]
	v_mfma_f32_16x16x4_f32 v[60:63], v225, v127, v[60:63]
	v_mfma_f32_16x16x4_f32 v[64:67], v225, v131, v[64:67]
	v_mfma_f32_16x16x4_f32 v[68:71], v225, v221, v[68:71]
	v_mfma_f32_16x16x4_f32 v[56:59], v226, v124, v[56:59]
	v_mfma_f32_16x16x4_f32 v[60:63], v226, v128, v[60:63]
	v_mfma_f32_16x16x4_f32 v[64:67], v226, v132, v[64:67]
	v_mfma_f32_16x16x4_f32 v[68:71], v226, v222, v[68:71]
	v_mfma_f32_16x16x4_f32 v[56:59], v227, v125, v[56:59]
	v_mfma_f32_16x16x4_f32 v[60:63], v227, v129, v[60:63]
	v_mfma_f32_16x16x4_f32 v[64:67], v227, v133, v[64:67]
	v_mfma_f32_16x16x4_f32 v[68:71], v227, v223, v[68:71]
	s_nop 7
	s_nop 7
	s_nop 7
	v_lshlrev_b32_e32 v216, 9, v2
	s_and_b32 s17, s14, 1
	s_lshl_b32 s17, s17, 6
	v_add3_u32 v216, v216, v0, s17
	v_lshlrev_b32_e32 v216, 1, v216
	s_lshr_b32 s17, s14, 1
	s_lshl_b32 s17, s17, 14
	v_add_u32_e32 v216, s17, v216
	s_mov_b64 s[72:73], s[92:93]
	v_cvt_pk_bf16_f32 v3, v8, v8
	global_store_short v216, v3, s[72:73] offset:0
	v_cvt_pk_bf16_f32 v217, v12, v12
	global_store_short v216, v217, s[72:73] offset:32
	v_cvt_pk_bf16_f32 v218, v16, v16
	global_store_short v216, v218, s[72:73] offset:64
	v_cvt_pk_bf16_f32 v230, v20, v20
	global_store_short v216, v230, s[72:73] offset:96
	v_cvt_pk_bf16_f32 v3, v9, v9
	global_store_short v216, v3, s[72:73] offset:256
	v_cvt_pk_bf16_f32 v217, v13, v13
	global_store_short v216, v217, s[72:73] offset:288
	v_cvt_pk_bf16_f32 v218, v17, v17
	global_store_short v216, v218, s[72:73] offset:320
	v_cvt_pk_bf16_f32 v230, v21, v21
	global_store_short v216, v230, s[72:73] offset:352
	v_cvt_pk_bf16_f32 v3, v10, v10
	global_store_short v216, v3, s[72:73] offset:512
	v_cvt_pk_bf16_f32 v217, v14, v14
	global_store_short v216, v217, s[72:73] offset:544
	v_cvt_pk_bf16_f32 v218, v18, v18
	global_store_short v216, v218, s[72:73] offset:576
	v_cvt_pk_bf16_f32 v230, v22, v22
	global_store_short v216, v230, s[72:73] offset:608
	v_cvt_pk_bf16_f32 v3, v11, v11
	global_store_short v216, v3, s[72:73] offset:768
	v_cvt_pk_bf16_f32 v217, v15, v15
	global_store_short v216, v217, s[72:73] offset:800
	v_cvt_pk_bf16_f32 v218, v19, v19
	global_store_short v216, v218, s[72:73] offset:832
	v_cvt_pk_bf16_f32 v230, v23, v23
	global_store_short v216, v230, s[72:73] offset:864
	s_add_u32 s72, s72, 0x1000
	s_addc_u32 s73, s73, 0
	v_cvt_pk_bf16_f32 v3, v24, v24
	global_store_short v216, v3, s[72:73] offset:0
	v_cvt_pk_bf16_f32 v217, v28, v28
	global_store_short v216, v217, s[72:73] offset:32
	v_cvt_pk_bf16_f32 v218, v32, v32
	global_store_short v216, v218, s[72:73] offset:64
	v_cvt_pk_bf16_f32 v230, v36, v36
	global_store_short v216, v230, s[72:73] offset:96
	v_cvt_pk_bf16_f32 v3, v25, v25
	global_store_short v216, v3, s[72:73] offset:256
	v_cvt_pk_bf16_f32 v217, v29, v29
	global_store_short v216, v217, s[72:73] offset:288
	v_cvt_pk_bf16_f32 v218, v33, v33
	global_store_short v216, v218, s[72:73] offset:320
	v_cvt_pk_bf16_f32 v230, v37, v37
	global_store_short v216, v230, s[72:73] offset:352
	v_cvt_pk_bf16_f32 v3, v26, v26
	global_store_short v216, v3, s[72:73] offset:512
	v_cvt_pk_bf16_f32 v217, v30, v30
	global_store_short v216, v217, s[72:73] offset:544
	v_cvt_pk_bf16_f32 v218, v34, v34
	global_store_short v216, v218, s[72:73] offset:576
	v_cvt_pk_bf16_f32 v230, v38, v38
	global_store_short v216, v230, s[72:73] offset:608
	v_cvt_pk_bf16_f32 v3, v27, v27
	global_store_short v216, v3, s[72:73] offset:768
	v_cvt_pk_bf16_f32 v217, v31, v31
	global_store_short v216, v217, s[72:73] offset:800
	v_cvt_pk_bf16_f32 v218, v35, v35
	global_store_short v216, v218, s[72:73] offset:832
	v_cvt_pk_bf16_f32 v230, v39, v39
	global_store_short v216, v230, s[72:73] offset:864
	s_add_u32 s72, s72, 0x1000
	s_addc_u32 s73, s73, 0
	v_cvt_pk_bf16_f32 v3, v40, v40
	global_store_short v216, v3, s[72:73] offset:0
	v_cvt_pk_bf16_f32 v217, v44, v44
	global_store_short v216, v217, s[72:73] offset:32
	v_cvt_pk_bf16_f32 v218, v48, v48
	global_store_short v216, v218, s[72:73] offset:64
	v_cvt_pk_bf16_f32 v230, v52, v52
	global_store_short v216, v230, s[72:73] offset:96
	v_cvt_pk_bf16_f32 v3, v41, v41
	global_store_short v216, v3, s[72:73] offset:256
	v_cvt_pk_bf16_f32 v217, v45, v45
	global_store_short v216, v217, s[72:73] offset:288
	v_cvt_pk_bf16_f32 v218, v49, v49
	global_store_short v216, v218, s[72:73] offset:320
	v_cvt_pk_bf16_f32 v230, v53, v53
	global_store_short v216, v230, s[72:73] offset:352
	v_cvt_pk_bf16_f32 v3, v42, v42
	global_store_short v216, v3, s[72:73] offset:512
	v_cvt_pk_bf16_f32 v217, v46, v46
	global_store_short v216, v217, s[72:73] offset:544
	v_cvt_pk_bf16_f32 v218, v50, v50
	global_store_short v216, v218, s[72:73] offset:576
	v_cvt_pk_bf16_f32 v230, v54, v54
	global_store_short v216, v230, s[72:73] offset:608
	v_cvt_pk_bf16_f32 v3, v43, v43
	global_store_short v216, v3, s[72:73] offset:768
	v_cvt_pk_bf16_f32 v217, v47, v47
	global_store_short v216, v217, s[72:73] offset:800
	v_cvt_pk_bf16_f32 v218, v51, v51
	global_store_short v216, v218, s[72:73] offset:832
	v_cvt_pk_bf16_f32 v230, v55, v55
	global_store_short v216, v230, s[72:73] offset:864
	s_add_u32 s72, s72, 0x1000
	s_addc_u32 s73, s73, 0
	v_cvt_pk_bf16_f32 v3, v56, v56
	global_store_short v216, v3, s[72:73] offset:0
	v_cvt_pk_bf16_f32 v217, v60, v60
	global_store_short v216, v217, s[72:73] offset:32
	v_cvt_pk_bf16_f32 v218, v64, v64
	global_store_short v216, v218, s[72:73] offset:64
	v_cvt_pk_bf16_f32 v230, v68, v68
	global_store_short v216, v230, s[72:73] offset:96
	v_cvt_pk_bf16_f32 v3, v57, v57
	global_store_short v216, v3, s[72:73] offset:256
	v_cvt_pk_bf16_f32 v217, v61, v61
	global_store_short v216, v217, s[72:73] offset:288
	v_cvt_pk_bf16_f32 v218, v65, v65
	global_store_short v216, v218, s[72:73] offset:320
	v_cvt_pk_bf16_f32 v230, v69, v69
	global_store_short v216, v230, s[72:73] offset:352
	v_cvt_pk_bf16_f32 v3, v58, v58
	global_store_short v216, v3, s[72:73] offset:512
	v_cvt_pk_bf16_f32 v217, v62, v62
	global_store_short v216, v217, s[72:73] offset:544
	v_cvt_pk_bf16_f32 v218, v66, v66
	global_store_short v216, v218, s[72:73] offset:576
	v_cvt_pk_bf16_f32 v230, v70, v70
	global_store_short v216, v230, s[72:73] offset:608
	v_cvt_pk_bf16_f32 v3, v59, v59
	global_store_short v216, v3, s[72:73] offset:768
	v_cvt_pk_bf16_f32 v217, v63, v63
	global_store_short v216, v217, s[72:73] offset:800
	v_cvt_pk_bf16_f32 v218, v67, v67
	global_store_short v216, v218, s[72:73] offset:832
	v_cvt_pk_bf16_f32 v230, v71, v71
	global_store_short v216, v230, s[72:73] offset:864
	s_and_saveexec_b64 s[0:1], s[96:97]
	s_xor_b64 s[0:1], exec, s[0:1]
	s_cbranch_execz .LBB0_315
	ds_read_b32 v0, v1 offset:49916
	s_mov_b32 s65, s9
	v_readlane_b32 s68, v251, 8
	s_lshl_b64 s[14:15], s[64:65], 2
	v_readlane_b32 s76, v251, 16
	v_readlane_b32 s77, v251, 17
	s_add_u32 s14, s76, s14
	s_addc_u32 s15, s77, s15
	v_readlane_b32 s69, v251, 9
	v_readlane_b32 s70, v251, 10
	v_readlane_b32 s71, v251, 11
	v_readlane_b32 s72, v251, 12
	v_readlane_b32 s73, v251, 13
	v_readlane_b32 s74, v251, 14
	v_readlane_b32 s75, v251, 15
	v_readlane_b32 s78, v251, 18
	v_readlane_b32 s79, v251, 19
	v_readlane_b32 s80, v251, 20
	v_readlane_b32 s81, v251, 21
	v_readlane_b32 s82, v251, 22
	v_readlane_b32 s83, v251, 23
	s_waitcnt lgkmcnt(0)
	global_store_dword v1, v0, s[14:15]
